# P0 transposer loop reordered: transpose+stores of item i, then s_sleep 40, then the 8 loads of item i+1 (stores no longer queued behind the wave's own loads); on top of h1pf
# baseline (speedup 1.0000x reference)
; __device__ __forceinline__ void p0_prologue(const Ptrs& P, LAS unsigned char* lds, int vcu, int G, int tid) {
;     ...
;         for (int it = gw; it < NITEMS; it += NGW) {
;             const int nit = it + NGW; const bool has_n = nit < NITEMS;
;             f32x4 nv[8];
;             const TItem nxt = t_decode(P, has_n ? nit : it, lane); t_load(nxt, nv);
;     ...
;             asm volatile("s_waitcnt lgkmcnt(0)" ::: "memory");
; #pragma unroll
;             for (int j = 0; j < 8; ++j) v[j] = nv[j];
;             cur = nxt;
.LBB0_38:
	s_waitcnt lgkmcnt(0)
	s_sleep 40
	global_load_dwordx4 v[34:37], v[42:43], off nt
	global_load_dwordx4 v[38:41], v[44:45], off nt
	s_nop 0
	global_load_dwordx4 v[42:45], v[50:51], off nt
	global_load_dwordx4 v[46:49], v[52:53], off nt
	s_nop 0
	global_load_dwordx4 v[50:53], v[58:59], off nt
	global_load_dwordx4 v[54:57], v[60:61], off nt
	global_load_dwordx4 v[62:65], v[98:99], off nt
	global_load_dwordx4 v[58:61], v[100:101], off nt
	s_waitcnt vmcnt(0)
	v_mov_b64_e32 v[30:31], v[62:63]
	v_mov_b64_e32 v[26:27], v[34:35]
	v_mov_b64_e32 v[22:23], v[38:39]
	v_mov_b64_e32 v[18:19], v[42:43]
	v_mov_b64_e32 v[14:15], v[46:47]
	v_mov_b64_e32 v[10:11], v[50:51]
	v_mov_b64_e32 v[6:7], v[54:55]
	s_waitcnt lgkmcnt(0)
	v_mov_b64_e32 v[2:3], v[58:59]
	s_andn2_b64 vcc, exec, s[22:23]
	v_mov_b64_e32 v[32:33], v[64:65]
	v_mov_b64_e32 v[28:29], v[36:37]
	v_mov_b64_e32 v[24:25], v[40:41]
	v_mov_b64_e32 v[20:21], v[44:45]
	v_mov_b64_e32 v[16:17], v[48:49]
	v_mov_b64_e32 v[12:13], v[52:53]
	v_mov_b64_e32 v[8:9], v[56:57]
	v_mov_b64_e32 v[4:5], v[60:61]
	s_mov_b32 s51, s52
	s_mov_b64 s[18:19], s[24:25]
	s_cbranch_vccz .LBB0_65

; #define LAS __attribute__((address_space(3)))
; __device__ __forceinline__ void p0_prologue(const Ptrs& P, LAS unsigned char* lds, int vcu, int G, int tid) {
;     ...
;             const int c4 = 4 * (lane & 7), r8 = lane >> 3;
; #pragma unroll
;             for (int j = 0; j < 8; ++j) { LAS float* d = scr + (8 * j + r8) * 33 + c4; d[0] = v[j][0]; d[1] = v[j][1]; d[2] = v[j][2]; d[3] = v[j][3]; }
;             asm volatile("s_waitcnt lgkmcnt(0)" ::: "memory");
;             const int c = lane & 7;
;             if (cur.f8) {
; #pragma unroll
;                 for (int j = 0; j < 4; ++j) { const int n = (lane >> 3) + 8 * j; const LAS float* sp = scr + (8 * c) * 33 + n;
;                     int w0 = 0, w1 = 0;
;                     w0 = __builtin_amdgcn_cvt_pk_fp8_f32(sp[0 * 33] * F8_SW, sp[1 * 33] * F8_SW, w0, false); w0 = __builtin_amdgcn_cvt_pk_fp8_f32(sp[2 * 33] * F8_SW, sp[3 * 33] * F8_SW, w0, true);
;                     w1 = __builtin_amdgcn_cvt_pk_fp8_f32(sp[4 * 33] * F8_SW, sp[5 * 33] * F8_SW, w1, false); w1 = __builtin_amdgcn_cvt_pk_fp8_f32(sp[6 * 33] * F8_SW, sp[7 * 33] * F8_SW, w1, true);
;                     u32x2 o; o.x = (unsigned)w0; o.y = (unsigned)w1;
;                     *(u32x2*)((unsigned char*)cur.dst + (size_t)n * cur.ldk + 8 * c) = o; }
.LBB0_62:
	s_lshl_b32 s20, s26, 5
	v_lshl_add_u64 v[42:43], v[78:79], 0, s[20:21]
	v_lshl_add_u64 v[44:45], v[42:43], 0, s[20:21]
	v_lshl_add_u64 v[50:51], v[44:45], 0, s[20:21]
	v_lshl_add_u64 v[52:53], v[50:51], 0, s[20:21]
	v_lshl_add_u64 v[58:59], v[52:53], 0, s[20:21]
	v_lshl_add_u64 v[60:61], v[58:59], 0, s[20:21]
	v_lshl_add_u64 v[100:101], v[60:61], 0, s[20:21]
	v_mov_b64_e32 v[98:99], v[78:79]
	s_waitcnt vmcnt(12)
	ds_write2_b32 v85, v30, v31 offset1:1
	ds_write2_b32 v85, v32, v33 offset0:2 offset1:3
	v_add_u32_e32 v30, 0x420, v85
	ds_write2_b32 v30, v26, v27 offset1:1
	v_add_u32_e32 v26, 0x428, v85
	ds_write2_b32 v26, v28, v29 offset1:1
	v_add_u32_e32 v26, 0x840, v85
	ds_write2_b32 v26, v22, v23 offset1:1
	v_add_u32_e32 v22, 0x848, v85
	ds_write2_b32 v22, v24, v25 offset1:1
	v_add_u32_e32 v22, 0xc60, v85
	ds_write2_b32 v22, v18, v19 offset1:1
	v_add_u32_e32 v18, 0xc68, v85
	ds_write2_b32 v18, v20, v21 offset1:1
	v_add_u32_e32 v18, 0x1080, v85
	ds_write2_b32 v18, v14, v15 offset1:1
	v_add_u32_e32 v14, 0x1088, v85
	ds_write2_b32 v14, v16, v17 offset1:1
	v_add_u32_e32 v14, 0x14a0, v85
	ds_write2_b32 v14, v10, v11 offset1:1
	v_add_u32_e32 v10, 0x14a8, v85
	ds_write2_b32 v10, v12, v13 offset1:1
	v_add_u32_e32 v10, 0x18c0, v85
	ds_write2_b32 v10, v6, v7 offset1:1
	v_add_u32_e32 v6, 0x18c8, v85
	ds_write2_b32 v6, v8, v9 offset1:1
	v_add_u32_e32 v6, 0x1ce0, v85
	ds_write2_b32 v6, v2, v3 offset1:1
	v_add_u32_e32 v2, 0x1ce8, v85
	ds_write2_b32 v2, v4, v5 offset1:1
	s_waitcnt lgkmcnt(0)
	ds_read_b32 v2, v84
	s_cmp_eq_u32 s51, 0
	s_cbranch_scc1 .LBB0_64
	ds_read2_b32 v[4:5], v84 offset0:24 offset1:33
	ds_read2_b32 v[10:11], v84 offset0:57 offset1:66
	ds_read2_b32 v[12:13], v84 offset0:90 offset1:99
	s_waitcnt lgkmcnt(3)
	v_mul_f32_e32 v3, 0x43800000, v2
	v_mov_b32_e32 v8, v69
	s_waitcnt lgkmcnt(2)
	v_mul_f32_e32 v5, 0x43800000, v5
	ds_read2_b32 v[14:15], v84 offset0:123 offset1:132
	ds_read2_b32 v[16:17], v84 offset0:156 offset1:165
	v_cvt_pk_fp8_f32 v8, v3, v5
	s_waitcnt lgkmcnt(3)
	v_mul_f32_e32 v3, 0x43800000, v11
	s_waitcnt lgkmcnt(2)
	v_mul_f32_e32 v5, 0x43800000, v13
	ds_read2_b32 v[18:19], v84 offset0:189 offset1:198
	ds_read2_b32 v[20:21], v84 offset0:222 offset1:231
	v_cvt_pk_fp8_f32 v8, v3, v5 op_sel:[0,0,1]
	s_waitcnt lgkmcnt(3)
	v_mul_f32_e32 v3, 0x43800000, v15
	s_waitcnt lgkmcnt(2)
	v_mul_f32_e32 v5, 0x43800000, v17
	v_mov_b32_e32 v9, v69
	ds_read2_b32 v[22:23], v84 offset0:8 offset1:16
	ds_read2_b32 v[24:25], v84 offset0:41 offset1:49
	v_cvt_pk_fp8_f32 v9, v3, v5
	ds_read2_b32 v[28:29], v84 offset0:74 offset1:82
	ds_read2_b32 v[30:31], v84 offset0:107 offset1:115
	ds_read2_b32 v[32:33], v84 offset0:140 offset1:148
	ds_read2_b32 v[78:79], v84 offset0:173 offset1:181
	s_waitcnt lgkmcnt(7)
	v_mul_f32_e32 v3, 0x43800000, v19
	s_waitcnt lgkmcnt(6)
	v_mul_f32_e32 v5, 0x43800000, v21
	v_cvt_pk_fp8_f32 v9, v3, v5 op_sel:[0,0,1]
	s_waitcnt lgkmcnt(5)
	v_mul_f32_e32 v3, 0x43800000, v22
	s_waitcnt lgkmcnt(4)
	v_mul_f32_e32 v5, 0x43800000, v24
	v_mov_b32_e32 v26, v69
	ds_read2_b32 v[86:87], v84 offset0:206 offset1:214
	ds_read2_b32 v[88:89], v84 offset0:239 offset1:247
	v_cvt_pk_fp8_f32 v26, v3, v5
	s_waitcnt lgkmcnt(3)
	v_mul_f32_e32 v11, 0x43800000, v32
	s_waitcnt lgkmcnt(2)
	v_mul_f32_e32 v13, 0x43800000, v78
	v_mov_b32_e32 v27, v69
	v_cvt_pk_fp8_f32 v27, v11, v13
	v_mul_f32_e32 v3, 0x43800000, v28
	v_mul_f32_e32 v5, 0x43800000, v30
	v_cvt_pk_fp8_f32 v26, v3, v5 op_sel:[0,0,1]
	s_waitcnt lgkmcnt(1)
	v_mul_f32_e32 v3, 0x43800000, v86
	s_waitcnt lgkmcnt(0)
	v_mul_f32_e32 v5, 0x43800000, v88
	v_cvt_pk_fp8_f32 v27, v3, v5 op_sel:[0,0,1]
	v_lshl_add_u64 v[6:7], s[18:19], 0, v[66:67]
	v_lshl_add_u64 v[92:93], v[6:7], 0, v[70:71]
	global_store_dwordx2 v[92:93], v[8:9], off sc1
	v_lshl_add_u64 v[8:9], v[6:7], 0, v[72:73]
	global_store_dwordx2 v[8:9], v[26:27], off sc1
	v_mul_f32_e32 v3, 0x43800000, v23
	v_mul_f32_e32 v5, 0x43800000, v25
	v_mov_b32_e32 v8, v69
	v_cvt_pk_fp8_f32 v8, v3, v5
	v_mul_f32_e32 v11, 0x43800000, v33
	v_mul_f32_e32 v13, 0x43800000, v79
	v_mov_b32_e32 v9, v69
	v_cvt_pk_fp8_f32 v9, v11, v13
	v_mul_f32_e32 v3, 0x43800000, v29
	v_mul_f32_e32 v5, 0x43800000, v31
	v_cvt_pk_fp8_f32 v8, v3, v5 op_sel:[0,0,1]
	v_mul_f32_e32 v3, 0x43800000, v87
	v_mul_f32_e32 v5, 0x43800000, v89
	v_cvt_pk_fp8_f32 v9, v3, v5 op_sel:[0,0,1]
	v_mul_f32_e32 v3, 0x43800000, v4
	v_mul_f32_e32 v5, 0x43800000, v10
	v_mov_b32_e32 v4, v69
	ds_read_b32 v13, v84 offset:1020
	v_cvt_pk_fp8_f32 v4, v3, v5
	v_mul_f32_e32 v3, 0x43800000, v12
	v_mul_f32_e32 v11, 0x43800000, v16
	v_mul_f32_e32 v12, 0x43800000, v18
	v_mov_b32_e32 v5, v69
	v_cvt_pk_fp8_f32 v5, v11, v12
	v_mul_f32_e32 v10, 0x43800000, v14
	v_cvt_pk_fp8_f32 v4, v3, v10 op_sel:[0,0,1]
	v_mul_f32_e32 v3, 0x43800000, v20
	s_waitcnt lgkmcnt(0)
	v_mul_f32_e32 v10, 0x43800000, v13
	v_cvt_pk_fp8_f32 v5, v3, v10 op_sel:[0,0,1]
	v_lshl_add_u64 v[10:11], v[6:7], 0, v[74:75]
	v_lshl_add_u64 v[6:7], v[6:7], 0, v[76:77]
	global_store_dwordx2 v[10:11], v[8:9], off sc1
	global_store_dwordx2 v[6:7], v[4:5], off sc1
	s_cbranch_execnz .LBB0_38
	s_branch .LBB0_37
